# LRU in-loop next-unit loads: two shared base addresses + immediate row offsets, no per-load predication (rows always valid for chunk>=2)
# baseline (speedup 1.0000x reference)
; __device__ __forceinline__ unsigned pk_bf16(float lo, float hi) { typedef __bf16 b2_t __attribute__((ext_vector_type(2))); f32x2 v = {lo, hi}; b2_t b = __builtin_convertvector(v, b2_t); return __builtin_bit_cast(unsigned, b); }
; __device__ __forceinline__ void lru_phase(LAS unsigned char* lds, const bf16* XB, const bf16* Y, bf16* HY, const bf16* WRt, const bf16* WIt,
;         const float* convw, const float* convb, const float* br, const float* bi, const float* lam, unsigned long long* gran, int G, int bid, int wave_s) {
;     ...
;         {
;             float cw[4][8], cb[8];
; #pragma unroll
;             for (int j = 0; j < 4; ++j) { const f32x4 c0v = *(const LAS f32x4*)(parL + j * 64 + cc), c1v = *(const LAS f32x4*)(parL + j * 64 + cc + 4);
;                 cw[j][0] = c0v[0]; cw[j][1] = c0v[1]; cw[j][2] = c0v[2]; cw[j][3] = c0v[3]; cw[j][4] = c1v[0]; cw[j][5] = c1v[1]; cw[j][6] = c1v[2]; cw[j][7] = c1v[3]; }
;             { const f32x4 c0v = *(const LAS f32x4*)(parL + 256 + cc), c1v = *(const LAS f32x4*)(parL + 256 + cc + 4);
;                 cb[0] = c0v[0]; cb[1] = c0v[1]; cb[2] = c0v[2]; cb[3] = c0v[3]; cb[4] = c1v[0]; cb[5] = c1v[1]; cb[6] = c1v[2]; cb[7] = c1v[3]; }
; #pragma unroll
;             for (int r = 0; r < 2; ++r) {
;                 const int t = st + 64 * r;
;                 float acc[8];
; #pragma unroll
;                 for (int e = 0; e < 8; ++e) acc[e] = cb[e];
; #pragma unroll
;                 for (int j = 0; j < 4; ++j) {
;                     const v4u x = xt[r][j];
;                     acc[0] += cw[j][0] * bf_lo(x.x); acc[1] += cw[j][1] * bf_hi(x.x); acc[2] += cw[j][2] * bf_lo(x.y); acc[3] += cw[j][3] * bf_hi(x.y);
;                     acc[4] += cw[j][4] * bf_lo(x.z); acc[5] += cw[j][5] * bf_hi(x.z); acc[6] += cw[j][6] * bf_lo(x.w); acc[7] += cw[j][7] * bf_hi(x.w);
;                 }
;                 *(LAS f32x4*)(xcF + t * 64 + cc) = (f32x4){acc[0], acc[1], acc[2], acc[3]}; *(LAS f32x4*)(xcF + t * 64 + cc + 4) = (f32x4){acc[4], acc[5], acc[6], acc[7]};
;                 v4u p; p.x = pk_bf16(acc[0], acc[1]); p.y = pk_bf16(acc[2], acc[3]); p.z = pk_bf16(acc[4], acc[5]); p.w = pk_bf16(acc[6], acc[7]);
;                 *(LAS v4u*)(xcB + t * KP + cc) = p;
;                 *(LAS v4u*)(yL + t * KP + cc) = yv[r];
;             }
;         }
;         if (unit + G < BATCH * 16 * NCH) LRU_LOAD_X(unit + G);
.LBB0_2122:
	s_waitcnt lgkmcnt(0)
	s_barrier
	ds_read_b128 v[0:3], v103
	ds_read_b128 v[4:7], v103 offset:16
	ds_read_b128 v[8:11], v103 offset:256
	ds_read_b128 v[12:15], v103 offset:272
	ds_read_b128 v[16:19], v103 offset:512
	ds_read_b128 v[20:23], v103 offset:528
	ds_read_b128 v[24:27], v104
	ds_read_b128 v[28:31], v103 offset:768
	ds_read_b128 v[88:91], v103 offset:784
	ds_read_b128 v[92:95], v104 offset:16
	s_waitcnt vmcnt(3)
	v_lshlrev_b32_e32 v96, 16, v40
	v_and_b32_e32 v97, 0xffff0000, v40
	s_waitcnt lgkmcnt(0)
	v_pk_fma_f32 v[96:97], v[0:1], v[96:97], v[24:25]
	v_lshlrev_b32_e32 v98, 16, v32
	v_and_b32_e32 v99, 0xffff0000, v32
	v_pk_fma_f32 v[96:97], v[8:9], v[98:99], v[96:97]
	v_lshlrev_b32_e32 v98, 16, v44
	v_and_b32_e32 v99, 0xffff0000, v44
	v_pk_fma_f32 v[96:97], v[16:17], v[98:99], v[96:97]
	v_lshlrev_b32_e32 v98, 16, v48
	v_and_b32_e32 v99, 0xffff0000, v48
	v_pk_fma_f32 v[96:97], v[28:29], v[98:99], v[96:97]
	v_lshlrev_b32_e32 v98, 16, v41
	v_and_b32_e32 v99, 0xffff0000, v41
	v_pk_fma_f32 v[98:99], v[2:3], v[98:99], v[26:27]
	v_lshlrev_b32_e32 v206, 16, v33
	v_and_b32_e32 v207, 0xffff0000, v33
	v_pk_fma_f32 v[98:99], v[10:11], v[206:207], v[98:99]
	v_lshlrev_b32_e32 v206, 16, v45
	v_and_b32_e32 v207, 0xffff0000, v45
	v_pk_fma_f32 v[98:99], v[18:19], v[206:207], v[98:99]
	v_lshlrev_b32_e32 v206, 16, v49
	v_and_b32_e32 v207, 0xffff0000, v49
	v_pk_fma_f32 v[98:99], v[30:31], v[206:207], v[98:99]
	v_lshlrev_b32_e32 v206, 16, v42
	v_and_b32_e32 v207, 0xffff0000, v42
	v_pk_fma_f32 v[206:207], v[4:5], v[206:207], v[92:93]
	v_lshlrev_b32_e32 v208, 16, v34
	v_and_b32_e32 v209, 0xffff0000, v34
	v_pk_fma_f32 v[206:207], v[12:13], v[208:209], v[206:207]
	v_lshlrev_b32_e32 v208, 16, v46
	v_and_b32_e32 v209, 0xffff0000, v46
	v_pk_fma_f32 v[206:207], v[20:21], v[208:209], v[206:207]
	v_lshlrev_b32_e32 v208, 16, v50
	v_and_b32_e32 v209, 0xffff0000, v50
	v_pk_fma_f32 v[206:207], v[88:89], v[208:209], v[206:207]
	v_lshlrev_b32_e32 v208, 16, v43
	v_and_b32_e32 v209, 0xffff0000, v43
	v_pk_fma_f32 v[208:209], v[6:7], v[208:209], v[94:95]
	v_lshlrev_b32_e32 v210, 16, v35
	v_and_b32_e32 v211, 0xffff0000, v35
	v_pk_fma_f32 v[208:209], v[14:15], v[210:211], v[208:209]
	v_lshlrev_b32_e32 v210, 16, v47
	v_and_b32_e32 v211, 0xffff0000, v47
	v_pk_fma_f32 v[208:209], v[22:23], v[210:211], v[208:209]
	v_lshlrev_b32_e32 v210, 16, v51
	v_and_b32_e32 v211, 0xffff0000, v51
	v_pk_fma_f32 v[208:209], v[90:91], v[210:211], v[208:209]
	v_add_u32_e32 v65, v105, v115
	ds_write_b128 v65, v[96:99]
	ds_write_b128 v65, v[206:209] offset:16
	v_cvt_pk_bf16_f32 v96, v96, v97
	v_cvt_pk_bf16_f32 v97, v98, v99
	v_cvt_pk_bf16_f32 v98, v206, v207
	v_cvt_pk_bf16_f32 v99, v208, v209
	v_add_u32_e32 v206, v106, v114
	ds_write_b128 v206, v[96:99]
	ds_write_b128 v116, v[36:39]
	s_waitcnt vmcnt(2)
	v_lshlrev_b32_e32 v96, 16, v56
	v_and_b32_e32 v97, 0xffff0000, v56
	v_pk_fma_f32 v[0:1], v[0:1], v[96:97], v[24:25]
	v_lshlrev_b32_e32 v24, 16, v60
	v_and_b32_e32 v25, 0xffff0000, v60
	v_pk_fma_f32 v[0:1], v[8:9], v[24:25], v[0:1]
	v_lshlrev_b32_e32 v8, 16, v66
	v_and_b32_e32 v9, 0xffff0000, v66
	v_pk_fma_f32 v[0:1], v[16:17], v[8:9], v[0:1]
	v_lshlrev_b32_e32 v8, 16, v70
	v_and_b32_e32 v9, 0xffff0000, v70
	v_pk_fma_f32 v[0:1], v[28:29], v[8:9], v[0:1]
	v_lshlrev_b32_e32 v8, 16, v57
	v_and_b32_e32 v9, 0xffff0000, v57
	v_pk_fma_f32 v[2:3], v[2:3], v[8:9], v[26:27]
	v_lshlrev_b32_e32 v8, 16, v61
	v_and_b32_e32 v9, 0xffff0000, v61
	v_pk_fma_f32 v[2:3], v[10:11], v[8:9], v[2:3]
	v_lshlrev_b32_e32 v8, 16, v67
	v_and_b32_e32 v9, 0xffff0000, v67
	v_pk_fma_f32 v[2:3], v[18:19], v[8:9], v[2:3]
	v_lshlrev_b32_e32 v8, 16, v71
	v_and_b32_e32 v9, 0xffff0000, v71
	v_pk_fma_f32 v[2:3], v[30:31], v[8:9], v[2:3]
	v_lshlrev_b32_e32 v8, 16, v58
	v_and_b32_e32 v9, 0xffff0000, v58
	v_pk_fma_f32 v[4:5], v[4:5], v[8:9], v[92:93]
	v_lshlrev_b32_e32 v8, 16, v62
	v_and_b32_e32 v9, 0xffff0000, v62
	v_pk_fma_f32 v[4:5], v[12:13], v[8:9], v[4:5]
	v_lshlrev_b32_e32 v8, 16, v68
	v_and_b32_e32 v9, 0xffff0000, v68
	v_pk_fma_f32 v[4:5], v[20:21], v[8:9], v[4:5]
	v_lshlrev_b32_e32 v8, 16, v72
	v_and_b32_e32 v9, 0xffff0000, v72
	v_pk_fma_f32 v[4:5], v[88:89], v[8:9], v[4:5]
	v_lshlrev_b32_e32 v8, 16, v59
	v_and_b32_e32 v9, 0xffff0000, v59
	v_pk_fma_f32 v[6:7], v[6:7], v[8:9], v[94:95]
	v_lshlrev_b32_e32 v8, 16, v63
	v_and_b32_e32 v9, 0xffff0000, v63
	v_pk_fma_f32 v[6:7], v[14:15], v[8:9], v[6:7]
	v_lshlrev_b32_e32 v8, 16, v69
	v_and_b32_e32 v9, 0xffff0000, v69
	s_add_i32 s93, s84, s46
	v_pk_fma_f32 v[6:7], v[22:23], v[8:9], v[6:7]
	v_lshlrev_b32_e32 v8, 16, v73
	v_and_b32_e32 v9, 0xffff0000, v73
	s_cmpk_gt_i32 s93, 0x7ff
	v_pk_fma_f32 v[6:7], v[90:91], v[8:9], v[6:7]
	s_cselect_b64 s[58:59], -1, 0
	ds_write_b128 v190, v[0:3]
	ds_write_b128 v190, v[4:7] offset:16
	v_cvt_pk_bf16_f32 v0, v0, v1
	v_cvt_pk_bf16_f32 v1, v2, v3
	v_cvt_pk_bf16_f32 v2, v4, v5
	v_cvt_pk_bf16_f32 v3, v6, v7
	s_and_b64 vcc, exec, s[58:59]
	ds_write_b128 v117, v[0:3]
	ds_write_b128 v118, v[52:55]
	s_cbranch_vccnz .LBB0_2140
	s_and_b32 s6, s93, 0xffffff80
	s_lshl_b32 s7, s93, 7
	s_and_b32 s60, s7, 0x3800
	v_add_u32_e32 v8, s6, v100
	v_add_u32_e32 v4, s60, v8
	s_and_b32 s6, s7, 0x780
	s_mov_b32 s7, s42
	v_ashrrev_i32_e32 v5, 31, v4
	v_lshl_add_u64 v[6:7], v[76:77], 0, s[6:7]
	v_lshl_add_u64 v[0:1], v[78:79], 0, s[6:7]
	v_lshlrev_b64 v[2:3], 11, v[4:5]
	s_mov_b32 s60, 0xfffff800
	s_mov_b32 s61, -1
	v_lshl_add_u64 v[6:7], v[6:7], 0, v[2:3]
	v_lshl_add_u64 v[0:1], v[0:1], 0, v[2:3]
	global_load_dwordx4 v[36:39], v[6:7], off
	v_lshl_add_u64 v[0:1], v[0:1], 0, s[60:61]
	s_mov_b32 s60, 0x20000
	s_mov_b32 s61, 0
	global_load_dwordx4 v[40:43], v[0:1], off offset:-4096
	global_load_dwordx4 v[32:35], v[0:1], off offset:-2048
	global_load_dwordx4 v[44:47], v[0:1], off
	global_load_dwordx4 v[48:51], v[0:1], off offset:2048
	v_lshl_add_u64 v[6:7], v[6:7], 0, s[60:61]
	v_lshl_add_u64 v[2:3], v[0:1], 0, s[60:61]
	global_load_dwordx4 v[52:55], v[6:7], off
	global_load_dwordx4 v[56:59], v[2:3], off offset:-4096
	global_load_dwordx4 v[60:63], v[2:3], off offset:-2048
	global_load_dwordx4 v[66:69], v[2:3], off
	global_load_dwordx4 v[70:73], v[2:3], off offset:2048
